# scan consumer schedule: dependent dot/butterfly chain issued tightly with vector fillers only, LDS reads batched after the state update
# speedup vs baseline: 1.0519x; 1.0181x over previous
; __device__ __forceinline__ void rwkv_prompt_unit(const Params& p, int l, int b, int h, int ibase, float* sf) {
;     ...
;             const float* bf_ = sf + (c & 1) * 12288 + jg; float* sY = sYb + (c & 1) * 512; const float* vb_ = sf + (c & 1) * 12288 + 6144 + ibase + rl;
;             f32x4 R[2], W[2], K[2], A[2], B[2]; float V[2];
;     ...
;             RW_LOAD(R, W, K, A, B, V, 0);
;             float pyprev = 0.f;
; #pragma unroll
;             for (int g = 0; g < 16; ++g) {
;                 f32x4 Rn[2], Wn[2], Kn[2], An[2], Bn[2]; float Vn[2];
;                 if (g + 1 < 16) RW_LOAD(Rn, Wn, Kn, An, Bn, Vn, g + 1);
;                 __builtin_amdgcn_sched_barrier(0);
; #pragma unroll
;                 for (int u = 0; u < 2; ++u) {
;                     const f32x2v a01 = {A[u].x, A[u].y}, a23 = {A[u].z, A[u].w}, w01 = {W[u].x, W[u].y}, w23 = {W[u].z, W[u].w}, b01 = {B[u].x, B[u].y}, b23 = {B[u].z, B[u].w};
;                     const f32x2v k01 = {K[u].x, K[u].y}, k23 = {K[u].z, K[u].w}, r01 = {R[u].x, R[u].y}, r23 = {R[u].z, R[u].w};
;                     f32x2v pa = S01 * a01; pa = __builtin_elementwise_fma(S23, a23, pa);
;                     float ra = pa.x + pa.y, rb = pyprev;
;                     ra += dppf<0xB1, 0xF>(ra); rb += dppf<0xB1, 0xF>(rb);
;                     ra += dppf<0x4E, 0xF>(ra); rb += dppf<0x4E, 0xF>(rb);
;                     ra += dppf<0x124, 0xF>(ra); rb += dppf<0x124, 0xF>(rb);
;                     ra += dppf<0x128, 0xF>(ra); rb += dppf<0x128, 0xF>(rb);
;                     if ((g * 2 + u) > 0 && (lane & 15) == 0) sY[(g * 2 + u - 1) * 16 + rl] = rb;
;                     const f32x2v sa2 = {ra, ra}, v2 = {V[u], V[u]};
;                     S01 = __builtin_elementwise_fma(S01, w01, __builtin_elementwise_fma(sa2, b01, v2 * k01));
;                     S23 = __builtin_elementwise_fma(S23, w23, __builtin_elementwise_fma(sa2, b23, v2 * k23));
;                     f32x2v py = S01 * r01; py = __builtin_elementwise_fma(S23, r23, py);
;                     pyprev = py.x + py.y;
;                 }
;                 __builtin_amdgcn_sched_barrier(0);
;                 if (g + 1 < 16) {
; #pragma unroll
;                     for (int u = 0; u < 2; ++u) { R[u] = Rn[u]; W[u] = Wn[u]; K[u] = Kn[u]; A[u] = An[u]; B[u] = Bn[u]; V[u] = Vn[u]; }
.LBB0_964:
	s_and_b64 vcc, exec, s[8:9]
	s_cbranch_vccz .LBB0_1029
	s_setprio 0
	s_and_b32 s8, s15, 1
	s_mul_i32 s9, s8, 0xc000
	v_lshl_add_u32 v212, v176, 2, s9
	s_add_i32 s9, s9, s11
	v_lshl_add_u32 v213, v210, 2, s9
	ds_read_b128 v[50:53], v212 offset:32768
	ds_read_b128 v[62:65], v212 offset:16384
	ds_read_b128 v[54:57], v212 offset:8192
	ds_read_b128 v[58:61], v212 offset:40960
	ds_read_b128 v[66:69], v212 offset:0
	ds_read2st64_b32 v[110:111], v213 offset0:96 offset1:97
	ds_read_b128 v[70:73], v212 offset:33024
	ds_read_b128 v[82:85], v212 offset:16640
	ds_read_b128 v[74:77], v212 offset:8448
	ds_read_b128 v[78:81], v212 offset:41216
	ds_read_b128 v[86:89], v212 offset:256
	s_lshl_b32 s8, s8, 11
	s_add_i32 s8, s8, 0x18000
	v_lshl_add_u32 v211, v210, 2, s8
	v_and_b32_e32 v137, 3, v207
	v_lshl_add_u32 v211, v137, 6, v211
	s_add_i32 s8, s8, 0x1000
	v_and_b32_e32 v137, 63, v207
	v_lshl_add_u32 v137, v137, 2, s8
	v_and_b32_e32 v186, 15, v207
	v_cmp_gt_u32_e32 vcc, 4, v186
	s_nop 1
	v_cndmask_b32_e32 v211, v137, v211, vcc
	v_and_b32_e32 v186, 1, v207
	v_cmp_ne_u32_e64 s[8:9], 0, v186
	v_and_b32_e32 v186, 2, v207
	v_cmp_ne_u32_e32 vcc, 0, v186
	s_waitcnt lgkmcnt(5)
	v_pk_mul_f32 v[114:115], v[46:47], v[50:51]
	s_nop 0
	v_pk_fma_f32 v[114:115], v[48:49], v[52:53], v[114:115]
	s_nop 0
	v_add_f32_e32 v116, v114, v115
	v_pk_mul_f32 v[120:121], v[62:63], v[110:111] op_sel_hi:[1,0]
	s_nop 0
	v_add_f32_dpp v116, v116, v116 quad_perm:[1,0,3,2] row_mask:0xf bank_mask:0xf bound_ctrl:1
	v_pk_mul_f32 v[122:123], v[64:65], v[110:111] op_sel_hi:[1,0]
	v_pk_fma_f32 v[124:125], v[46:47], v[54:55], v[120:121]
	v_add_f32_dpp v116, v116, v116 quad_perm:[2,3,0,1] row_mask:0xf bank_mask:0xf bound_ctrl:1
	v_pk_fma_f32 v[126:127], v[48:49], v[56:57], v[122:123]
	s_nop 0
	v_add_f32_dpp v116, v116, v116 row_ror:4 row_mask:0xf bank_mask:0xf bound_ctrl:1
	s_nop 1
	v_add_f32_dpp v116, v116, v116 row_ror:8 row_mask:0xf bank_mask:0xf bound_ctrl:1
	v_pk_fma_f32 v[46:47], v[116:117], v[58:59], v[124:125] op_sel_hi:[0,1,1]
	v_pk_fma_f32 v[48:49], v[116:117], v[60:61], v[126:127] op_sel_hi:[0,1,1]
	ds_read_b128 v[90:93], v212 offset:33280
	ds_read_b128 v[102:105], v212 offset:16896
	ds_read_b128 v[94:97], v212 offset:8704
	ds_read_b128 v[98:101], v212 offset:41472
	ds_read_b128 v[106:109], v212 offset:512
	ds_read2st64_b32 v[112:113], v213 offset0:98 offset1:99
	s_waitcnt lgkmcnt(6)
	v_pk_mul_f32 v[114:115], v[46:47], v[70:71]
	v_pk_mul_f32 v[118:119], v[46:47], v[66:67]
	v_pk_fma_f32 v[114:115], v[48:49], v[72:73], v[114:115]
	v_pk_fma_f32 v[118:119], v[48:49], v[68:69], v[118:119]
	v_add_f32_e32 v116, v114, v115
	v_add_f32_e32 v129, v118, v119
	v_pk_mul_f32 v[120:121], v[82:83], v[110:111] op_sel:[0,1] op_sel_hi:[1,1]
	v_add_f32_dpp v116, v116, v116 quad_perm:[1,0,3,2] row_mask:0xf bank_mask:0xf bound_ctrl:1
	v_pk_mul_f32 v[122:123], v[84:85], v[110:111] op_sel:[0,1] op_sel_hi:[1,1]
	v_pk_fma_f32 v[124:125], v[46:47], v[74:75], v[120:121]
	v_add_f32_dpp v116, v116, v116 quad_perm:[2,3,0,1] row_mask:0xf bank_mask:0xf bound_ctrl:1
	v_pk_fma_f32 v[126:127], v[48:49], v[76:77], v[122:123]
	s_nop 0
	v_add_f32_dpp v116, v116, v116 row_ror:4 row_mask:0xf bank_mask:0xf bound_ctrl:1
	s_nop 1
	v_add_f32_dpp v116, v116, v116 row_ror:8 row_mask:0xf bank_mask:0xf bound_ctrl:1
	v_pk_fma_f32 v[46:47], v[116:117], v[78:79], v[124:125] op_sel_hi:[0,1,1]
	v_pk_fma_f32 v[48:49], v[116:117], v[80:81], v[126:127] op_sel_hi:[0,1,1]
	ds_read_b128 v[50:53], v212 offset:33536
	ds_read_b128 v[62:65], v212 offset:17152
	ds_read_b128 v[54:57], v212 offset:8960
	ds_read_b128 v[58:61], v212 offset:41728
	ds_read_b128 v[66:69], v212 offset:768
	s_waitcnt lgkmcnt(5)
	v_pk_mul_f32 v[114:115], v[46:47], v[90:91]
	v_pk_mul_f32 v[118:119], v[46:47], v[86:87]
	v_pk_fma_f32 v[114:115], v[48:49], v[92:93], v[114:115]
	v_pk_fma_f32 v[118:119], v[48:49], v[88:89], v[118:119]
	v_add_f32_e32 v116, v114, v115
	v_add_f32_e32 v130, v118, v119
	v_pk_mul_f32 v[120:121], v[102:103], v[112:113] op_sel_hi:[1,0]
	v_add_f32_dpp v116, v116, v116 quad_perm:[1,0,3,2] row_mask:0xf bank_mask:0xf bound_ctrl:1
	v_pk_mul_f32 v[122:123], v[104:105], v[112:113] op_sel_hi:[1,0]
	v_pk_fma_f32 v[124:125], v[46:47], v[94:95], v[120:121]
	v_add_f32_dpp v116, v116, v116 quad_perm:[2,3,0,1] row_mask:0xf bank_mask:0xf bound_ctrl:1
	v_pk_fma_f32 v[126:127], v[48:49], v[96:97], v[122:123]
	s_nop 0
	v_add_f32_dpp v116, v116, v116 row_ror:4 row_mask:0xf bank_mask:0xf bound_ctrl:1
	s_nop 1
	v_add_f32_dpp v116, v116, v116 row_ror:8 row_mask:0xf bank_mask:0xf bound_ctrl:1
	v_pk_fma_f32 v[46:47], v[116:117], v[98:99], v[124:125] op_sel_hi:[0,1,1]
	v_pk_fma_f32 v[48:49], v[116:117], v[100:101], v[126:127] op_sel_hi:[0,1,1]
	ds_read_b128 v[70:73], v212 offset:33792
	ds_read_b128 v[82:85], v212 offset:17408
	ds_read_b128 v[74:77], v212 offset:9216
	ds_read_b128 v[78:81], v212 offset:41984
	ds_read_b128 v[86:89], v212 offset:1024
	ds_read2st64_b32 v[110:111], v213 offset0:100 offset1:101
	s_waitcnt lgkmcnt(6)
	v_pk_mul_f32 v[114:115], v[46:47], v[50:51]
	v_pk_mul_f32 v[118:119], v[46:47], v[106:107]
	v_pk_fma_f32 v[114:115], v[48:49], v[52:53], v[114:115]
	v_pk_fma_f32 v[118:119], v[48:49], v[108:109], v[118:119]
	v_add_f32_e32 v116, v114, v115
	v_add_f32_e32 v131, v118, v119
	v_pk_mul_f32 v[120:121], v[62:63], v[112:113] op_sel:[0,1] op_sel_hi:[1,1]
	v_add_f32_dpp v116, v116, v116 quad_perm:[1,0,3,2] row_mask:0xf bank_mask:0xf bound_ctrl:1
	v_pk_mul_f32 v[122:123], v[64:65], v[112:113] op_sel:[0,1] op_sel_hi:[1,1]
	v_pk_fma_f32 v[124:125], v[46:47], v[54:55], v[120:121]
	v_add_f32_dpp v116, v116, v116 quad_perm:[2,3,0,1] row_mask:0xf bank_mask:0xf bound_ctrl:1
	v_pk_fma_f32 v[126:127], v[48:49], v[56:57], v[122:123]
	s_nop 0
	v_add_f32_dpp v116, v116, v116 row_ror:4 row_mask:0xf bank_mask:0xf bound_ctrl:1
	s_nop 1
	v_add_f32_dpp v116, v116, v116 row_ror:8 row_mask:0xf bank_mask:0xf bound_ctrl:1
	v_pk_fma_f32 v[46:47], v[116:117], v[58:59], v[124:125] op_sel_hi:[0,1,1]
	v_pk_fma_f32 v[48:49], v[116:117], v[60:61], v[126:127] op_sel_hi:[0,1,1]
	ds_read_b128 v[90:93], v212 offset:34048
	ds_read_b128 v[102:105], v212 offset:17664
	ds_read_b128 v[94:97], v212 offset:9472
	ds_read_b128 v[98:101], v212 offset:42240
	ds_read_b128 v[106:109], v212 offset:1280
	s_waitcnt lgkmcnt(5)
; __device__ __forceinline__ void rwkv_prompt_unit(const Params& p, int l, int b, int h, int ibase, float* sf) {
;     ...
;             for (int g = 0; g < 16; ++g) {
;                 f32x4 Rn[2], Wn[2], Kn[2], An[2], Bn[2]; float Vn[2];
;                 if (g + 1 < 16) RW_LOAD(Rn, Wn, Kn, An, Bn, Vn, g + 1);
;                 __builtin_amdgcn_sched_barrier(0);
; #pragma unroll
;                 for (int u = 0; u < 2; ++u) {
;                     const f32x2v a01 = {A[u].x, A[u].y}, a23 = {A[u].z, A[u].w}, w01 = {W[u].x, W[u].y}, w23 = {W[u].z, W[u].w}, b01 = {B[u].x, B[u].y}, b23 = {B[u].z, B[u].w};
;                     const f32x2v k01 = {K[u].x, K[u].y}, k23 = {K[u].z, K[u].w}, r01 = {R[u].x, R[u].y}, r23 = {R[u].z, R[u].w};
;                     f32x2v pa = S01 * a01; pa = __builtin_elementwise_fma(S23, a23, pa);
;                     float ra = pa.x + pa.y, rb = pyprev;
;                     ra += dppf<0xB1, 0xF>(ra); rb += dppf<0xB1, 0xF>(rb);
;                     ra += dppf<0x4E, 0xF>(ra); rb += dppf<0x4E, 0xF>(rb);
;                     ra += dppf<0x124, 0xF>(ra); rb += dppf<0x124, 0xF>(rb);
;                     ra += dppf<0x128, 0xF>(ra); rb += dppf<0x128, 0xF>(rb);
;                     if ((g * 2 + u) > 0 && (lane & 15) == 0) sY[(g * 2 + u - 1) * 16 + rl] = rb;
;                     const f32x2v sa2 = {ra, ra}, v2 = {V[u], V[u]};
;                     S01 = __builtin_elementwise_fma(S01, w01, __builtin_elementwise_fma(sa2, b01, v2 * k01));
;                     S23 = __builtin_elementwise_fma(S23, w23, __builtin_elementwise_fma(sa2, b23, v2 * k23));
;                     f32x2v py = S01 * r01; py = __builtin_elementwise_fma(S23, r23, py);
;                     pyprev = py.x + py.y;
;                 }
;                 __builtin_amdgcn_sched_barrier(0);
;                 if (g + 1 < 16) {
; #pragma unroll
;                     for (int u = 0; u < 2; ++u) { R[u] = Rn[u]; W[u] = Wn[u]; K[u] = Kn[u]; A[u] = An[u]; B[u] = Bn[u]; V[u] = Vn[u]; }
	v_pk_mul_f32 v[114:115], v[46:47], v[70:71]
	v_pk_mul_f32 v[118:119], v[46:47], v[66:67]
	v_pk_fma_f32 v[114:115], v[48:49], v[72:73], v[114:115]
	v_pk_fma_f32 v[118:119], v[48:49], v[68:69], v[118:119]
	v_add_f32_e32 v116, v114, v115
	v_add_f32_e32 v132, v118, v119
	v_pk_mul_f32 v[120:121], v[82:83], v[110:111] op_sel_hi:[1,0]
	v_add_f32_dpp v116, v116, v116 quad_perm:[1,0,3,2] row_mask:0xf bank_mask:0xf bound_ctrl:1
	v_pk_mul_f32 v[122:123], v[84:85], v[110:111] op_sel_hi:[1,0]
	v_pk_fma_f32 v[124:125], v[46:47], v[74:75], v[120:121]
	v_add_f32_dpp v116, v116, v116 quad_perm:[2,3,0,1] row_mask:0xf bank_mask:0xf bound_ctrl:1
	v_pk_fma_f32 v[126:127], v[48:49], v[76:77], v[122:123]
	v_cndmask_b32_e64 v137, v129, v130, s[8:9]
	v_add_f32_dpp v116, v116, v116 row_ror:4 row_mask:0xf bank_mask:0xf bound_ctrl:1
	v_cndmask_b32_e64 v186, v130, v129, s[8:9]
	s_nop 1
	v_add_f32_dpp v187, v186, v137 quad_perm:[1,0,3,2] row_mask:0xf bank_mask:0xf bound_ctrl:1
	v_add_f32_dpp v116, v116, v116 row_ror:8 row_mask:0xf bank_mask:0xf bound_ctrl:1
	v_pk_fma_f32 v[46:47], v[116:117], v[78:79], v[124:125] op_sel_hi:[0,1,1]
	v_pk_fma_f32 v[48:49], v[116:117], v[80:81], v[126:127] op_sel_hi:[0,1,1]
	ds_read_b128 v[50:53], v212 offset:34304
	ds_read_b128 v[62:65], v212 offset:17920
	ds_read_b128 v[54:57], v212 offset:9728
	ds_read_b128 v[58:61], v212 offset:42496
	ds_read_b128 v[66:69], v212 offset:1536
	ds_read2st64_b32 v[112:113], v213 offset0:102 offset1:103
	s_waitcnt lgkmcnt(6)
	v_pk_mul_f32 v[114:115], v[46:47], v[90:91]
	v_pk_mul_f32 v[118:119], v[46:47], v[86:87]
	v_pk_fma_f32 v[114:115], v[48:49], v[92:93], v[114:115]
	v_pk_fma_f32 v[118:119], v[48:49], v[88:89], v[118:119]
	v_add_f32_e32 v116, v114, v115
	v_add_f32_e32 v133, v118, v119
	v_pk_mul_f32 v[120:121], v[102:103], v[110:111] op_sel:[0,1] op_sel_hi:[1,1]
	v_add_f32_dpp v116, v116, v116 quad_perm:[1,0,3,2] row_mask:0xf bank_mask:0xf bound_ctrl:1
	v_pk_mul_f32 v[122:123], v[104:105], v[110:111] op_sel:[0,1] op_sel_hi:[1,1]
	v_pk_fma_f32 v[124:125], v[46:47], v[94:95], v[120:121]
	v_add_f32_dpp v116, v116, v116 quad_perm:[2,3,0,1] row_mask:0xf bank_mask:0xf bound_ctrl:1
	v_pk_fma_f32 v[126:127], v[48:49], v[96:97], v[122:123]
	v_cndmask_b32_e64 v137, v131, v132, s[8:9]
	v_add_f32_dpp v116, v116, v116 row_ror:4 row_mask:0xf bank_mask:0xf bound_ctrl:1
	v_cndmask_b32_e64 v186, v132, v131, s[8:9]
	s_nop 1
	v_add_f32_dpp v188, v186, v137 quad_perm:[1,0,3,2] row_mask:0xf bank_mask:0xf bound_ctrl:1
	v_add_f32_dpp v116, v116, v116 row_ror:8 row_mask:0xf bank_mask:0xf bound_ctrl:1
	v_pk_fma_f32 v[46:47], v[116:117], v[98:99], v[124:125] op_sel_hi:[0,1,1]
	v_pk_fma_f32 v[48:49], v[116:117], v[100:101], v[126:127] op_sel_hi:[0,1,1]
	ds_read_b128 v[70:73], v212 offset:34560
	ds_read_b128 v[82:85], v212 offset:18176
	ds_read_b128 v[74:77], v212 offset:9984
	ds_read_b128 v[78:81], v212 offset:42752
	ds_read_b128 v[86:89], v212 offset:1792
	s_waitcnt lgkmcnt(5)
	v_pk_mul_f32 v[114:115], v[46:47], v[50:51]
	v_pk_mul_f32 v[118:119], v[46:47], v[106:107]
	v_pk_fma_f32 v[114:115], v[48:49], v[52:53], v[114:115]
	v_pk_fma_f32 v[118:119], v[48:49], v[108:109], v[118:119]
	v_add_f32_e32 v116, v114, v115
	v_add_f32_e32 v134, v118, v119
	v_pk_mul_f32 v[120:121], v[62:63], v[112:113] op_sel_hi:[1,0]
	v_add_f32_dpp v116, v116, v116 quad_perm:[1,0,3,2] row_mask:0xf bank_mask:0xf bound_ctrl:1
	v_pk_mul_f32 v[122:123], v[64:65], v[112:113] op_sel_hi:[1,0]
	v_pk_fma_f32 v[124:125], v[46:47], v[54:55], v[120:121]
	v_add_f32_dpp v116, v116, v116 quad_perm:[2,3,0,1] row_mask:0xf bank_mask:0xf bound_ctrl:1
	v_pk_fma_f32 v[126:127], v[48:49], v[56:57], v[122:123]
	v_cndmask_b32_e32 v137, v187, v188, vcc
	v_add_f32_dpp v116, v116, v116 row_ror:4 row_mask:0xf bank_mask:0xf bound_ctrl:1
	v_cndmask_b32_e32 v186, v188, v187, vcc
	s_nop 1
	v_add_f32_dpp v189, v186, v137 quad_perm:[2,3,0,1] row_mask:0xf bank_mask:0xf bound_ctrl:1
	v_add_f32_dpp v116, v116, v116 row_ror:8 row_mask:0xf bank_mask:0xf bound_ctrl:1
	v_pk_fma_f32 v[46:47], v[116:117], v[58:59], v[124:125] op_sel_hi:[0,1,1]
	v_pk_fma_f32 v[48:49], v[116:117], v[60:61], v[126:127] op_sel_hi:[0,1,1]
	ds_read_b128 v[90:93], v212 offset:34816
	ds_read_b128 v[102:105], v212 offset:18432
	ds_read_b128 v[94:97], v212 offset:10240
	ds_read_b128 v[98:101], v212 offset:43008
	ds_read_b128 v[106:109], v212 offset:2048
	ds_read2st64_b32 v[110:111], v213 offset0:104 offset1:105
	s_waitcnt lgkmcnt(6)
	v_pk_mul_f32 v[114:115], v[46:47], v[70:71]
	v_pk_mul_f32 v[118:119], v[46:47], v[66:67]
	v_pk_fma_f32 v[114:115], v[48:49], v[72:73], v[114:115]
	v_pk_fma_f32 v[118:119], v[48:49], v[68:69], v[118:119]
	v_add_f32_e32 v116, v114, v115
	v_add_f32_e32 v135, v118, v119
	v_pk_mul_f32 v[120:121], v[82:83], v[112:113] op_sel:[0,1] op_sel_hi:[1,1]
	v_add_f32_dpp v116, v116, v116 quad_perm:[1,0,3,2] row_mask:0xf bank_mask:0xf bound_ctrl:1
	v_pk_mul_f32 v[122:123], v[84:85], v[112:113] op_sel:[0,1] op_sel_hi:[1,1]
	v_pk_fma_f32 v[124:125], v[46:47], v[74:75], v[120:121]
	v_add_f32_dpp v116, v116, v116 quad_perm:[2,3,0,1] row_mask:0xf bank_mask:0xf bound_ctrl:1
	v_pk_fma_f32 v[126:127], v[48:49], v[76:77], v[122:123]
	v_add_f32_dpp v189, v189, v189 row_ror:4 row_mask:0xf bank_mask:0xf bound_ctrl:1
	v_add_f32_dpp v116, v116, v116 row_ror:4 row_mask:0xf bank_mask:0xf bound_ctrl:1
	s_nop 0
	v_add_f32_dpp v189, v189, v189 row_ror:8 row_mask:0xf bank_mask:0xf bound_ctrl:1
	ds_write_b32 v211, v189 offset:0
	v_add_f32_dpp v116, v116, v116 row_ror:8 row_mask:0xf bank_mask:0xf bound_ctrl:1
	v_pk_fma_f32 v[46:47], v[116:117], v[78:79], v[124:125] op_sel_hi:[0,1,1]
	v_pk_fma_f32 v[48:49], v[116:117], v[80:81], v[126:127] op_sel_hi:[0,1,1]
	ds_read_b128 v[50:53], v212 offset:35072
	ds_read_b128 v[62:65], v212 offset:18688
	ds_read_b128 v[54:57], v212 offset:10496
	ds_read_b128 v[58:61], v212 offset:43264
	ds_read_b128 v[66:69], v212 offset:2304
	s_waitcnt lgkmcnt(6)
; __device__ __forceinline__ void rwkv_prompt_unit(const Params& p, int l, int b, int h, int ibase, float* sf) {
;     ...
;             for (int g = 0; g < 16; ++g) {
;                 f32x4 Rn[2], Wn[2], Kn[2], An[2], Bn[2]; float Vn[2];
;                 if (g + 1 < 16) RW_LOAD(Rn, Wn, Kn, An, Bn, Vn, g + 1);
;                 __builtin_amdgcn_sched_barrier(0);
; #pragma unroll
;                 for (int u = 0; u < 2; ++u) {
;                     const f32x2v a01 = {A[u].x, A[u].y}, a23 = {A[u].z, A[u].w}, w01 = {W[u].x, W[u].y}, w23 = {W[u].z, W[u].w}, b01 = {B[u].x, B[u].y}, b23 = {B[u].z, B[u].w};
;                     const f32x2v k01 = {K[u].x, K[u].y}, k23 = {K[u].z, K[u].w}, r01 = {R[u].x, R[u].y}, r23 = {R[u].z, R[u].w};
;                     f32x2v pa = S01 * a01; pa = __builtin_elementwise_fma(S23, a23, pa);
;                     float ra = pa.x + pa.y, rb = pyprev;
;                     ra += dppf<0xB1, 0xF>(ra); rb += dppf<0xB1, 0xF>(rb);
;                     ra += dppf<0x4E, 0xF>(ra); rb += dppf<0x4E, 0xF>(rb);
;                     ra += dppf<0x124, 0xF>(ra); rb += dppf<0x124, 0xF>(rb);
;                     ra += dppf<0x128, 0xF>(ra); rb += dppf<0x128, 0xF>(rb);
;                     if ((g * 2 + u) > 0 && (lane & 15) == 0) sY[(g * 2 + u - 1) * 16 + rl] = rb;
;                     const f32x2v sa2 = {ra, ra}, v2 = {V[u], V[u]};
;                     S01 = __builtin_elementwise_fma(S01, w01, __builtin_elementwise_fma(sa2, b01, v2 * k01));
;                     S23 = __builtin_elementwise_fma(S23, w23, __builtin_elementwise_fma(sa2, b23, v2 * k23));
;                     f32x2v py = S01 * r01; py = __builtin_elementwise_fma(S23, r23, py);
;                     pyprev = py.x + py.y;
;                 }
;                 __builtin_amdgcn_sched_barrier(0);
;                 if (g + 1 < 16) {
; #pragma unroll
;                     for (int u = 0; u < 2; ++u) { R[u] = Rn[u]; W[u] = Wn[u]; K[u] = Kn[u]; A[u] = An[u]; B[u] = Bn[u]; V[u] = Vn[u]; }
	v_pk_mul_f32 v[114:115], v[46:47], v[90:91]
	v_pk_mul_f32 v[118:119], v[46:47], v[86:87]
	v_pk_fma_f32 v[114:115], v[48:49], v[92:93], v[114:115]
	v_pk_fma_f32 v[118:119], v[48:49], v[88:89], v[118:119]
	v_add_f32_e32 v116, v114, v115
	v_add_f32_e32 v136, v118, v119
	v_pk_mul_f32 v[120:121], v[102:103], v[110:111] op_sel_hi:[1,0]
	v_add_f32_dpp v116, v116, v116 quad_perm:[1,0,3,2] row_mask:0xf bank_mask:0xf bound_ctrl:1
	v_pk_mul_f32 v[122:123], v[104:105], v[110:111] op_sel_hi:[1,0]
	v_pk_fma_f32 v[124:125], v[46:47], v[94:95], v[120:121]
	v_add_f32_dpp v116, v116, v116 quad_perm:[2,3,0,1] row_mask:0xf bank_mask:0xf bound_ctrl:1
	v_pk_fma_f32 v[126:127], v[48:49], v[96:97], v[122:123]
	v_cndmask_b32_e64 v137, v133, v134, s[8:9]
	v_add_f32_dpp v116, v116, v116 row_ror:4 row_mask:0xf bank_mask:0xf bound_ctrl:1
	v_cndmask_b32_e64 v186, v134, v133, s[8:9]
	s_nop 1
	v_add_f32_dpp v187, v186, v137 quad_perm:[1,0,3,2] row_mask:0xf bank_mask:0xf bound_ctrl:1
	v_add_f32_dpp v116, v116, v116 row_ror:8 row_mask:0xf bank_mask:0xf bound_ctrl:1
	v_pk_fma_f32 v[46:47], v[116:117], v[98:99], v[124:125] op_sel_hi:[0,1,1]
	v_pk_fma_f32 v[48:49], v[116:117], v[100:101], v[126:127] op_sel_hi:[0,1,1]
	ds_read_b128 v[70:73], v212 offset:35328
	ds_read_b128 v[82:85], v212 offset:18944
	ds_read_b128 v[74:77], v212 offset:10752
	ds_read_b128 v[78:81], v212 offset:43520
	ds_read_b128 v[86:89], v212 offset:2560
	ds_read2st64_b32 v[112:113], v213 offset0:106 offset1:107
	s_waitcnt lgkmcnt(6)
	v_pk_mul_f32 v[114:115], v[46:47], v[50:51]
	v_pk_mul_f32 v[118:119], v[46:47], v[106:107]
	v_pk_fma_f32 v[114:115], v[48:49], v[52:53], v[114:115]
	v_pk_fma_f32 v[118:119], v[48:49], v[108:109], v[118:119]
	v_add_f32_e32 v116, v114, v115
	v_add_f32_e32 v129, v118, v119
	v_pk_mul_f32 v[120:121], v[62:63], v[110:111] op_sel:[0,1] op_sel_hi:[1,1]
	v_add_f32_dpp v116, v116, v116 quad_perm:[1,0,3,2] row_mask:0xf bank_mask:0xf bound_ctrl:1
	v_pk_mul_f32 v[122:123], v[64:65], v[110:111] op_sel:[0,1] op_sel_hi:[1,1]
	v_pk_fma_f32 v[124:125], v[46:47], v[54:55], v[120:121]
	v_add_f32_dpp v116, v116, v116 quad_perm:[2,3,0,1] row_mask:0xf bank_mask:0xf bound_ctrl:1
	v_pk_fma_f32 v[126:127], v[48:49], v[56:57], v[122:123]
	v_cndmask_b32_e64 v137, v135, v136, s[8:9]
	v_add_f32_dpp v116, v116, v116 row_ror:4 row_mask:0xf bank_mask:0xf bound_ctrl:1
	v_cndmask_b32_e64 v186, v136, v135, s[8:9]
	s_nop 1
	v_add_f32_dpp v188, v186, v137 quad_perm:[1,0,3,2] row_mask:0xf bank_mask:0xf bound_ctrl:1
	v_add_f32_dpp v116, v116, v116 row_ror:8 row_mask:0xf bank_mask:0xf bound_ctrl:1
	v_pk_fma_f32 v[46:47], v[116:117], v[58:59], v[124:125] op_sel_hi:[0,1,1]
	v_pk_fma_f32 v[48:49], v[116:117], v[60:61], v[126:127] op_sel_hi:[0,1,1]
	ds_read_b128 v[90:93], v212 offset:35584
	ds_read_b128 v[102:105], v212 offset:19200
	ds_read_b128 v[94:97], v212 offset:11008
	ds_read_b128 v[98:101], v212 offset:43776
	ds_read_b128 v[106:109], v212 offset:2816
	s_waitcnt lgkmcnt(5)
	v_pk_mul_f32 v[114:115], v[46:47], v[70:71]
	v_pk_mul_f32 v[118:119], v[46:47], v[66:67]
	v_pk_fma_f32 v[114:115], v[48:49], v[72:73], v[114:115]
	v_pk_fma_f32 v[118:119], v[48:49], v[68:69], v[118:119]
	v_add_f32_e32 v116, v114, v115
	v_add_f32_e32 v130, v118, v119
	v_pk_mul_f32 v[120:121], v[82:83], v[112:113] op_sel_hi:[1,0]
	v_add_f32_dpp v116, v116, v116 quad_perm:[1,0,3,2] row_mask:0xf bank_mask:0xf bound_ctrl:1
	v_pk_mul_f32 v[122:123], v[84:85], v[112:113] op_sel_hi:[1,0]
	v_pk_fma_f32 v[124:125], v[46:47], v[74:75], v[120:121]
	v_add_f32_dpp v116, v116, v116 quad_perm:[2,3,0,1] row_mask:0xf bank_mask:0xf bound_ctrl:1
	v_pk_fma_f32 v[126:127], v[48:49], v[76:77], v[122:123]
	v_cndmask_b32_e32 v137, v187, v188, vcc
	v_add_f32_dpp v116, v116, v116 row_ror:4 row_mask:0xf bank_mask:0xf bound_ctrl:1
	v_cndmask_b32_e32 v186, v188, v187, vcc
	s_nop 1
	v_add_f32_dpp v189, v186, v137 quad_perm:[2,3,0,1] row_mask:0xf bank_mask:0xf bound_ctrl:1
	v_add_f32_dpp v116, v116, v116 row_ror:8 row_mask:0xf bank_mask:0xf bound_ctrl:1
	v_pk_fma_f32 v[46:47], v[116:117], v[78:79], v[124:125] op_sel_hi:[0,1,1]
	v_pk_fma_f32 v[48:49], v[116:117], v[80:81], v[126:127] op_sel_hi:[0,1,1]
	ds_read_b128 v[50:53], v212 offset:35840
	ds_read_b128 v[62:65], v212 offset:19456
	ds_read_b128 v[54:57], v212 offset:11264
	ds_read_b128 v[58:61], v212 offset:44032
	ds_read_b128 v[66:69], v212 offset:3072
	ds_read2st64_b32 v[110:111], v213 offset0:108 offset1:109
	s_waitcnt lgkmcnt(6)
	v_pk_mul_f32 v[114:115], v[46:47], v[90:91]
	v_pk_mul_f32 v[118:119], v[46:47], v[86:87]
	v_pk_fma_f32 v[114:115], v[48:49], v[92:93], v[114:115]
	v_pk_fma_f32 v[118:119], v[48:49], v[88:89], v[118:119]
	v_add_f32_e32 v116, v114, v115
	v_add_f32_e32 v131, v118, v119
	v_pk_mul_f32 v[120:121], v[102:103], v[112:113] op_sel:[0,1] op_sel_hi:[1,1]
	v_add_f32_dpp v116, v116, v116 quad_perm:[1,0,3,2] row_mask:0xf bank_mask:0xf bound_ctrl:1
	v_pk_mul_f32 v[122:123], v[104:105], v[112:113] op_sel:[0,1] op_sel_hi:[1,1]
	v_pk_fma_f32 v[124:125], v[46:47], v[94:95], v[120:121]
	v_add_f32_dpp v116, v116, v116 quad_perm:[2,3,0,1] row_mask:0xf bank_mask:0xf bound_ctrl:1
	v_pk_fma_f32 v[126:127], v[48:49], v[96:97], v[122:123]
	v_add_f32_dpp v189, v189, v189 row_ror:4 row_mask:0xf bank_mask:0xf bound_ctrl:1
	v_add_f32_dpp v116, v116, v116 row_ror:4 row_mask:0xf bank_mask:0xf bound_ctrl:1
	s_nop 0
	v_add_f32_dpp v189, v189, v189 row_ror:8 row_mask:0xf bank_mask:0xf bound_ctrl:1
	ds_write_b32 v211, v189 offset:256
	v_add_f32_dpp v116, v116, v116 row_ror:8 row_mask:0xf bank_mask:0xf bound_ctrl:1
	v_pk_fma_f32 v[46:47], v[116:117], v[98:99], v[124:125] op_sel_hi:[0,1,1]
	v_pk_fma_f32 v[48:49], v[116:117], v[100:101], v[126:127] op_sel_hi:[0,1,1]
	ds_read_b128 v[70:73], v212 offset:36096
	ds_read_b128 v[82:85], v212 offset:19712
	ds_read_b128 v[74:77], v212 offset:11520
	ds_read_b128 v[78:81], v212 offset:44288
	ds_read_b128 v[86:89], v212 offset:3328
	s_waitcnt lgkmcnt(6)
; __device__ __forceinline__ void rwkv_prompt_unit(const Params& p, int l, int b, int h, int ibase, float* sf) {
;     ...
;             for (int g = 0; g < 16; ++g) {
;                 f32x4 Rn[2], Wn[2], Kn[2], An[2], Bn[2]; float Vn[2];
;                 if (g + 1 < 16) RW_LOAD(Rn, Wn, Kn, An, Bn, Vn, g + 1);
;                 __builtin_amdgcn_sched_barrier(0);
; #pragma unroll
;                 for (int u = 0; u < 2; ++u) {
;                     const f32x2v a01 = {A[u].x, A[u].y}, a23 = {A[u].z, A[u].w}, w01 = {W[u].x, W[u].y}, w23 = {W[u].z, W[u].w}, b01 = {B[u].x, B[u].y}, b23 = {B[u].z, B[u].w};
;                     const f32x2v k01 = {K[u].x, K[u].y}, k23 = {K[u].z, K[u].w}, r01 = {R[u].x, R[u].y}, r23 = {R[u].z, R[u].w};
;                     f32x2v pa = S01 * a01; pa = __builtin_elementwise_fma(S23, a23, pa);
;                     float ra = pa.x + pa.y, rb = pyprev;
;                     ra += dppf<0xB1, 0xF>(ra); rb += dppf<0xB1, 0xF>(rb);
;                     ra += dppf<0x4E, 0xF>(ra); rb += dppf<0x4E, 0xF>(rb);
;                     ra += dppf<0x124, 0xF>(ra); rb += dppf<0x124, 0xF>(rb);
;                     ra += dppf<0x128, 0xF>(ra); rb += dppf<0x128, 0xF>(rb);
;                     if ((g * 2 + u) > 0 && (lane & 15) == 0) sY[(g * 2 + u - 1) * 16 + rl] = rb;
;                     const f32x2v sa2 = {ra, ra}, v2 = {V[u], V[u]};
;                     S01 = __builtin_elementwise_fma(S01, w01, __builtin_elementwise_fma(sa2, b01, v2 * k01));
;                     S23 = __builtin_elementwise_fma(S23, w23, __builtin_elementwise_fma(sa2, b23, v2 * k23));
;                     f32x2v py = S01 * r01; py = __builtin_elementwise_fma(S23, r23, py);
;                     pyprev = py.x + py.y;
;                 }
;                 __builtin_amdgcn_sched_barrier(0);
;                 if (g + 1 < 16) {
; #pragma unroll
;                     for (int u = 0; u < 2; ++u) { R[u] = Rn[u]; W[u] = Wn[u]; K[u] = Kn[u]; A[u] = An[u]; B[u] = Bn[u]; V[u] = Vn[u]; }
	v_pk_mul_f32 v[114:115], v[46:47], v[50:51]
	v_pk_mul_f32 v[118:119], v[46:47], v[106:107]
	v_pk_fma_f32 v[114:115], v[48:49], v[52:53], v[114:115]
	v_pk_fma_f32 v[118:119], v[48:49], v[108:109], v[118:119]
	v_add_f32_e32 v116, v114, v115
	v_add_f32_e32 v132, v118, v119
	v_pk_mul_f32 v[120:121], v[62:63], v[110:111] op_sel_hi:[1,0]
	v_add_f32_dpp v116, v116, v116 quad_perm:[1,0,3,2] row_mask:0xf bank_mask:0xf bound_ctrl:1
	v_pk_mul_f32 v[122:123], v[64:65], v[110:111] op_sel_hi:[1,0]
	v_pk_fma_f32 v[124:125], v[46:47], v[54:55], v[120:121]
	v_add_f32_dpp v116, v116, v116 quad_perm:[2,3,0,1] row_mask:0xf bank_mask:0xf bound_ctrl:1
	v_pk_fma_f32 v[126:127], v[48:49], v[56:57], v[122:123]
	v_cndmask_b32_e64 v137, v129, v130, s[8:9]
	v_add_f32_dpp v116, v116, v116 row_ror:4 row_mask:0xf bank_mask:0xf bound_ctrl:1
	v_cndmask_b32_e64 v186, v130, v129, s[8:9]
	s_nop 1
	v_add_f32_dpp v187, v186, v137 quad_perm:[1,0,3,2] row_mask:0xf bank_mask:0xf bound_ctrl:1
	v_add_f32_dpp v116, v116, v116 row_ror:8 row_mask:0xf bank_mask:0xf bound_ctrl:1
	v_pk_fma_f32 v[46:47], v[116:117], v[58:59], v[124:125] op_sel_hi:[0,1,1]
	v_pk_fma_f32 v[48:49], v[116:117], v[60:61], v[126:127] op_sel_hi:[0,1,1]
	ds_read_b128 v[90:93], v212 offset:36352
	ds_read_b128 v[102:105], v212 offset:19968
	ds_read_b128 v[94:97], v212 offset:11776
	ds_read_b128 v[98:101], v212 offset:44544
	ds_read_b128 v[106:109], v212 offset:3584
	ds_read2st64_b32 v[112:113], v213 offset0:110 offset1:111
	s_waitcnt lgkmcnt(6)
	v_pk_mul_f32 v[114:115], v[46:47], v[70:71]
	v_pk_mul_f32 v[118:119], v[46:47], v[66:67]
	v_pk_fma_f32 v[114:115], v[48:49], v[72:73], v[114:115]
	v_pk_fma_f32 v[118:119], v[48:49], v[68:69], v[118:119]
	v_add_f32_e32 v116, v114, v115
	v_add_f32_e32 v133, v118, v119
	v_pk_mul_f32 v[120:121], v[82:83], v[110:111] op_sel:[0,1] op_sel_hi:[1,1]
	v_add_f32_dpp v116, v116, v116 quad_perm:[1,0,3,2] row_mask:0xf bank_mask:0xf bound_ctrl:1
	v_pk_mul_f32 v[122:123], v[84:85], v[110:111] op_sel:[0,1] op_sel_hi:[1,1]
	v_pk_fma_f32 v[124:125], v[46:47], v[74:75], v[120:121]
	v_add_f32_dpp v116, v116, v116 quad_perm:[2,3,0,1] row_mask:0xf bank_mask:0xf bound_ctrl:1
	v_pk_fma_f32 v[126:127], v[48:49], v[76:77], v[122:123]
	v_cndmask_b32_e64 v137, v131, v132, s[8:9]
	v_add_f32_dpp v116, v116, v116 row_ror:4 row_mask:0xf bank_mask:0xf bound_ctrl:1
	v_cndmask_b32_e64 v186, v132, v131, s[8:9]
	s_nop 1
	v_add_f32_dpp v188, v186, v137 quad_perm:[1,0,3,2] row_mask:0xf bank_mask:0xf bound_ctrl:1
	v_add_f32_dpp v116, v116, v116 row_ror:8 row_mask:0xf bank_mask:0xf bound_ctrl:1
	v_pk_fma_f32 v[46:47], v[116:117], v[78:79], v[124:125] op_sel_hi:[0,1,1]
	v_pk_fma_f32 v[48:49], v[116:117], v[80:81], v[126:127] op_sel_hi:[0,1,1]
	ds_read_b128 v[50:53], v212 offset:36608
	ds_read_b128 v[62:65], v212 offset:20224
	ds_read_b128 v[54:57], v212 offset:12032
	ds_read_b128 v[58:61], v212 offset:44800
	ds_read_b128 v[66:69], v212 offset:3840
	s_waitcnt lgkmcnt(5)
	v_pk_mul_f32 v[114:115], v[46:47], v[90:91]
	v_pk_mul_f32 v[118:119], v[46:47], v[86:87]
	v_pk_fma_f32 v[114:115], v[48:49], v[92:93], v[114:115]
	v_pk_fma_f32 v[118:119], v[48:49], v[88:89], v[118:119]
	v_add_f32_e32 v116, v114, v115
	v_add_f32_e32 v134, v118, v119
	v_pk_mul_f32 v[120:121], v[102:103], v[112:113] op_sel_hi:[1,0]
	v_add_f32_dpp v116, v116, v116 quad_perm:[1,0,3,2] row_mask:0xf bank_mask:0xf bound_ctrl:1
	v_pk_mul_f32 v[122:123], v[104:105], v[112:113] op_sel_hi:[1,0]
	v_pk_fma_f32 v[124:125], v[46:47], v[94:95], v[120:121]
	v_add_f32_dpp v116, v116, v116 quad_perm:[2,3,0,1] row_mask:0xf bank_mask:0xf bound_ctrl:1
	v_pk_fma_f32 v[126:127], v[48:49], v[96:97], v[122:123]
	v_cndmask_b32_e32 v137, v187, v188, vcc
	v_add_f32_dpp v116, v116, v116 row_ror:4 row_mask:0xf bank_mask:0xf bound_ctrl:1
	v_cndmask_b32_e32 v186, v188, v187, vcc
	s_nop 1
	v_add_f32_dpp v189, v186, v137 quad_perm:[2,3,0,1] row_mask:0xf bank_mask:0xf bound_ctrl:1
	v_add_f32_dpp v116, v116, v116 row_ror:8 row_mask:0xf bank_mask:0xf bound_ctrl:1
	v_pk_fma_f32 v[46:47], v[116:117], v[98:99], v[124:125] op_sel_hi:[0,1,1]
	v_pk_fma_f32 v[48:49], v[116:117], v[100:101], v[126:127] op_sel_hi:[0,1,1]
	ds_read_b128 v[70:73], v212 offset:36864
	ds_read_b128 v[82:85], v212 offset:20480
	ds_read_b128 v[74:77], v212 offset:12288
	ds_read_b128 v[78:81], v212 offset:45056
	ds_read_b128 v[86:89], v212 offset:4096
	ds_read2st64_b32 v[110:111], v213 offset0:112 offset1:113
	s_waitcnt lgkmcnt(6)
	v_pk_mul_f32 v[114:115], v[46:47], v[50:51]
	v_pk_mul_f32 v[118:119], v[46:47], v[106:107]
	v_pk_fma_f32 v[114:115], v[48:49], v[52:53], v[114:115]
	v_pk_fma_f32 v[118:119], v[48:49], v[108:109], v[118:119]
	v_add_f32_e32 v116, v114, v115
	v_add_f32_e32 v135, v118, v119
	v_pk_mul_f32 v[120:121], v[62:63], v[112:113] op_sel:[0,1] op_sel_hi:[1,1]
	v_add_f32_dpp v116, v116, v116 quad_perm:[1,0,3,2] row_mask:0xf bank_mask:0xf bound_ctrl:1
	v_pk_mul_f32 v[122:123], v[64:65], v[112:113] op_sel:[0,1] op_sel_hi:[1,1]
	v_pk_fma_f32 v[124:125], v[46:47], v[54:55], v[120:121]
	v_add_f32_dpp v116, v116, v116 quad_perm:[2,3,0,1] row_mask:0xf bank_mask:0xf bound_ctrl:1
	v_pk_fma_f32 v[126:127], v[48:49], v[56:57], v[122:123]
	v_add_f32_dpp v189, v189, v189 row_ror:4 row_mask:0xf bank_mask:0xf bound_ctrl:1
	v_add_f32_dpp v116, v116, v116 row_ror:4 row_mask:0xf bank_mask:0xf bound_ctrl:1
	s_nop 0
	v_add_f32_dpp v189, v189, v189 row_ror:8 row_mask:0xf bank_mask:0xf bound_ctrl:1
	ds_write_b32 v211, v189 offset:512
	v_add_f32_dpp v116, v116, v116 row_ror:8 row_mask:0xf bank_mask:0xf bound_ctrl:1
	v_pk_fma_f32 v[46:47], v[116:117], v[58:59], v[124:125] op_sel_hi:[0,1,1]
	v_pk_fma_f32 v[48:49], v[116:117], v[60:61], v[126:127] op_sel_hi:[0,1,1]
	ds_read_b128 v[90:93], v212 offset:37120
	ds_read_b128 v[102:105], v212 offset:20736
	ds_read_b128 v[94:97], v212 offset:12544
	ds_read_b128 v[98:101], v212 offset:45312
	ds_read_b128 v[106:109], v212 offset:4352
	s_waitcnt lgkmcnt(6)
; __device__ __forceinline__ void rwkv_prompt_unit(const Params& p, int l, int b, int h, int ibase, float* sf) {
;     ...
;             for (int g = 0; g < 16; ++g) {
;                 f32x4 Rn[2], Wn[2], Kn[2], An[2], Bn[2]; float Vn[2];
;                 if (g + 1 < 16) RW_LOAD(Rn, Wn, Kn, An, Bn, Vn, g + 1);
;                 __builtin_amdgcn_sched_barrier(0);
; #pragma unroll
;                 for (int u = 0; u < 2; ++u) {
;                     const f32x2v a01 = {A[u].x, A[u].y}, a23 = {A[u].z, A[u].w}, w01 = {W[u].x, W[u].y}, w23 = {W[u].z, W[u].w}, b01 = {B[u].x, B[u].y}, b23 = {B[u].z, B[u].w};
;                     const f32x2v k01 = {K[u].x, K[u].y}, k23 = {K[u].z, K[u].w}, r01 = {R[u].x, R[u].y}, r23 = {R[u].z, R[u].w};
;                     f32x2v pa = S01 * a01; pa = __builtin_elementwise_fma(S23, a23, pa);
;                     float ra = pa.x + pa.y, rb = pyprev;
;                     ra += dppf<0xB1, 0xF>(ra); rb += dppf<0xB1, 0xF>(rb);
;                     ra += dppf<0x4E, 0xF>(ra); rb += dppf<0x4E, 0xF>(rb);
;                     ra += dppf<0x124, 0xF>(ra); rb += dppf<0x124, 0xF>(rb);
;                     ra += dppf<0x128, 0xF>(ra); rb += dppf<0x128, 0xF>(rb);
;                     if ((g * 2 + u) > 0 && (lane & 15) == 0) sY[(g * 2 + u - 1) * 16 + rl] = rb;
;                     const f32x2v sa2 = {ra, ra}, v2 = {V[u], V[u]};
;                     S01 = __builtin_elementwise_fma(S01, w01, __builtin_elementwise_fma(sa2, b01, v2 * k01));
;                     S23 = __builtin_elementwise_fma(S23, w23, __builtin_elementwise_fma(sa2, b23, v2 * k23));
;                     f32x2v py = S01 * r01; py = __builtin_elementwise_fma(S23, r23, py);
;                     pyprev = py.x + py.y;
;                 }
;                 __builtin_amdgcn_sched_barrier(0);
;                 if (g + 1 < 16) {
; #pragma unroll
;                     for (int u = 0; u < 2; ++u) { R[u] = Rn[u]; W[u] = Wn[u]; K[u] = Kn[u]; A[u] = An[u]; B[u] = Bn[u]; V[u] = Vn[u]; }
	v_pk_mul_f32 v[114:115], v[46:47], v[70:71]
	v_pk_mul_f32 v[118:119], v[46:47], v[66:67]
	v_pk_fma_f32 v[114:115], v[48:49], v[72:73], v[114:115]
	v_pk_fma_f32 v[118:119], v[48:49], v[68:69], v[118:119]
	v_add_f32_e32 v116, v114, v115
	v_add_f32_e32 v136, v118, v119
	v_pk_mul_f32 v[120:121], v[82:83], v[110:111] op_sel_hi:[1,0]
	v_add_f32_dpp v116, v116, v116 quad_perm:[1,0,3,2] row_mask:0xf bank_mask:0xf bound_ctrl:1
	v_pk_mul_f32 v[122:123], v[84:85], v[110:111] op_sel_hi:[1,0]
	v_pk_fma_f32 v[124:125], v[46:47], v[74:75], v[120:121]
	v_add_f32_dpp v116, v116, v116 quad_perm:[2,3,0,1] row_mask:0xf bank_mask:0xf bound_ctrl:1
	v_pk_fma_f32 v[126:127], v[48:49], v[76:77], v[122:123]
	v_cndmask_b32_e64 v137, v133, v134, s[8:9]
	v_add_f32_dpp v116, v116, v116 row_ror:4 row_mask:0xf bank_mask:0xf bound_ctrl:1
	v_cndmask_b32_e64 v186, v134, v133, s[8:9]
	s_nop 1
	v_add_f32_dpp v187, v186, v137 quad_perm:[1,0,3,2] row_mask:0xf bank_mask:0xf bound_ctrl:1
	v_add_f32_dpp v116, v116, v116 row_ror:8 row_mask:0xf bank_mask:0xf bound_ctrl:1
	v_pk_fma_f32 v[46:47], v[116:117], v[78:79], v[124:125] op_sel_hi:[0,1,1]
	v_pk_fma_f32 v[48:49], v[116:117], v[80:81], v[126:127] op_sel_hi:[0,1,1]
	ds_read_b128 v[50:53], v212 offset:37376
	ds_read_b128 v[62:65], v212 offset:20992
	ds_read_b128 v[54:57], v212 offset:12800
	ds_read_b128 v[58:61], v212 offset:45568
	ds_read_b128 v[66:69], v212 offset:4608
	ds_read2st64_b32 v[112:113], v213 offset0:114 offset1:115
	s_waitcnt lgkmcnt(6)
	v_pk_mul_f32 v[114:115], v[46:47], v[90:91]
	v_pk_mul_f32 v[118:119], v[46:47], v[86:87]
	v_pk_fma_f32 v[114:115], v[48:49], v[92:93], v[114:115]
	v_pk_fma_f32 v[118:119], v[48:49], v[88:89], v[118:119]
	v_add_f32_e32 v116, v114, v115
	v_add_f32_e32 v129, v118, v119
	v_pk_mul_f32 v[120:121], v[102:103], v[110:111] op_sel:[0,1] op_sel_hi:[1,1]
	v_add_f32_dpp v116, v116, v116 quad_perm:[1,0,3,2] row_mask:0xf bank_mask:0xf bound_ctrl:1
	v_pk_mul_f32 v[122:123], v[104:105], v[110:111] op_sel:[0,1] op_sel_hi:[1,1]
	v_pk_fma_f32 v[124:125], v[46:47], v[94:95], v[120:121]
	v_add_f32_dpp v116, v116, v116 quad_perm:[2,3,0,1] row_mask:0xf bank_mask:0xf bound_ctrl:1
	v_pk_fma_f32 v[126:127], v[48:49], v[96:97], v[122:123]
	v_cndmask_b32_e64 v137, v135, v136, s[8:9]
	v_add_f32_dpp v116, v116, v116 row_ror:4 row_mask:0xf bank_mask:0xf bound_ctrl:1
	v_cndmask_b32_e64 v186, v136, v135, s[8:9]
	s_nop 1
	v_add_f32_dpp v188, v186, v137 quad_perm:[1,0,3,2] row_mask:0xf bank_mask:0xf bound_ctrl:1
	v_add_f32_dpp v116, v116, v116 row_ror:8 row_mask:0xf bank_mask:0xf bound_ctrl:1
	v_pk_fma_f32 v[46:47], v[116:117], v[98:99], v[124:125] op_sel_hi:[0,1,1]
	v_pk_fma_f32 v[48:49], v[116:117], v[100:101], v[126:127] op_sel_hi:[0,1,1]
	ds_read_b128 v[70:73], v212 offset:37632
	ds_read_b128 v[82:85], v212 offset:21248
	ds_read_b128 v[74:77], v212 offset:13056
	ds_read_b128 v[78:81], v212 offset:45824
	ds_read_b128 v[86:89], v212 offset:4864
	s_waitcnt lgkmcnt(5)
	v_pk_mul_f32 v[114:115], v[46:47], v[50:51]
	v_pk_mul_f32 v[118:119], v[46:47], v[106:107]
	v_pk_fma_f32 v[114:115], v[48:49], v[52:53], v[114:115]
	v_pk_fma_f32 v[118:119], v[48:49], v[108:109], v[118:119]
	v_add_f32_e32 v116, v114, v115
	v_add_f32_e32 v130, v118, v119
	v_pk_mul_f32 v[120:121], v[62:63], v[112:113] op_sel_hi:[1,0]
	v_add_f32_dpp v116, v116, v116 quad_perm:[1,0,3,2] row_mask:0xf bank_mask:0xf bound_ctrl:1
	v_pk_mul_f32 v[122:123], v[64:65], v[112:113] op_sel_hi:[1,0]
	v_pk_fma_f32 v[124:125], v[46:47], v[54:55], v[120:121]
	v_add_f32_dpp v116, v116, v116 quad_perm:[2,3,0,1] row_mask:0xf bank_mask:0xf bound_ctrl:1
	v_pk_fma_f32 v[126:127], v[48:49], v[56:57], v[122:123]
	v_cndmask_b32_e32 v137, v187, v188, vcc
	v_add_f32_dpp v116, v116, v116 row_ror:4 row_mask:0xf bank_mask:0xf bound_ctrl:1
	v_cndmask_b32_e32 v186, v188, v187, vcc
	s_nop 1
	v_add_f32_dpp v189, v186, v137 quad_perm:[2,3,0,1] row_mask:0xf bank_mask:0xf bound_ctrl:1
	v_add_f32_dpp v116, v116, v116 row_ror:8 row_mask:0xf bank_mask:0xf bound_ctrl:1
	v_pk_fma_f32 v[46:47], v[116:117], v[58:59], v[124:125] op_sel_hi:[0,1,1]
	v_pk_fma_f32 v[48:49], v[116:117], v[60:61], v[126:127] op_sel_hi:[0,1,1]
	ds_read_b128 v[90:93], v212 offset:37888
	ds_read_b128 v[102:105], v212 offset:21504
	ds_read_b128 v[94:97], v212 offset:13312
	ds_read_b128 v[98:101], v212 offset:46080
	ds_read_b128 v[106:109], v212 offset:5120
	ds_read2st64_b32 v[110:111], v213 offset0:116 offset1:117
	s_waitcnt lgkmcnt(6)
	v_pk_mul_f32 v[114:115], v[46:47], v[70:71]
	v_pk_mul_f32 v[118:119], v[46:47], v[66:67]
	v_pk_fma_f32 v[114:115], v[48:49], v[72:73], v[114:115]
	v_pk_fma_f32 v[118:119], v[48:49], v[68:69], v[118:119]
	v_add_f32_e32 v116, v114, v115
	v_add_f32_e32 v131, v118, v119
	v_pk_mul_f32 v[120:121], v[82:83], v[112:113] op_sel:[0,1] op_sel_hi:[1,1]
	v_add_f32_dpp v116, v116, v116 quad_perm:[1,0,3,2] row_mask:0xf bank_mask:0xf bound_ctrl:1
	v_pk_mul_f32 v[122:123], v[84:85], v[112:113] op_sel:[0,1] op_sel_hi:[1,1]
	v_pk_fma_f32 v[124:125], v[46:47], v[74:75], v[120:121]
	v_add_f32_dpp v116, v116, v116 quad_perm:[2,3,0,1] row_mask:0xf bank_mask:0xf bound_ctrl:1
	v_pk_fma_f32 v[126:127], v[48:49], v[76:77], v[122:123]
	v_add_f32_dpp v189, v189, v189 row_ror:4 row_mask:0xf bank_mask:0xf bound_ctrl:1
	v_add_f32_dpp v116, v116, v116 row_ror:4 row_mask:0xf bank_mask:0xf bound_ctrl:1
	s_nop 0
	v_add_f32_dpp v189, v189, v189 row_ror:8 row_mask:0xf bank_mask:0xf bound_ctrl:1
	ds_write_b32 v211, v189 offset:768
	v_add_f32_dpp v116, v116, v116 row_ror:8 row_mask:0xf bank_mask:0xf bound_ctrl:1
	v_pk_fma_f32 v[46:47], v[116:117], v[78:79], v[124:125] op_sel_hi:[0,1,1]
	v_pk_fma_f32 v[48:49], v[116:117], v[80:81], v[126:127] op_sel_hi:[0,1,1]
	ds_read_b128 v[50:53], v212 offset:38144
	ds_read_b128 v[62:65], v212 offset:21760
	ds_read_b128 v[54:57], v212 offset:13568
	ds_read_b128 v[58:61], v212 offset:46336
	ds_read_b128 v[66:69], v212 offset:5376
	s_waitcnt lgkmcnt(6)
; __device__ __forceinline__ void rwkv_prompt_unit(const Params& p, int l, int b, int h, int ibase, float* sf) {
;     ...
;             for (int g = 0; g < 16; ++g) {
;                 f32x4 Rn[2], Wn[2], Kn[2], An[2], Bn[2]; float Vn[2];
;                 if (g + 1 < 16) RW_LOAD(Rn, Wn, Kn, An, Bn, Vn, g + 1);
;                 __builtin_amdgcn_sched_barrier(0);
; #pragma unroll
;                 for (int u = 0; u < 2; ++u) {
;                     const f32x2v a01 = {A[u].x, A[u].y}, a23 = {A[u].z, A[u].w}, w01 = {W[u].x, W[u].y}, w23 = {W[u].z, W[u].w}, b01 = {B[u].x, B[u].y}, b23 = {B[u].z, B[u].w};
;                     const f32x2v k01 = {K[u].x, K[u].y}, k23 = {K[u].z, K[u].w}, r01 = {R[u].x, R[u].y}, r23 = {R[u].z, R[u].w};
;                     f32x2v pa = S01 * a01; pa = __builtin_elementwise_fma(S23, a23, pa);
;                     float ra = pa.x + pa.y, rb = pyprev;
;                     ra += dppf<0xB1, 0xF>(ra); rb += dppf<0xB1, 0xF>(rb);
;                     ra += dppf<0x4E, 0xF>(ra); rb += dppf<0x4E, 0xF>(rb);
;                     ra += dppf<0x124, 0xF>(ra); rb += dppf<0x124, 0xF>(rb);
;                     ra += dppf<0x128, 0xF>(ra); rb += dppf<0x128, 0xF>(rb);
;                     if ((g * 2 + u) > 0 && (lane & 15) == 0) sY[(g * 2 + u - 1) * 16 + rl] = rb;
;                     const f32x2v sa2 = {ra, ra}, v2 = {V[u], V[u]};
;                     S01 = __builtin_elementwise_fma(S01, w01, __builtin_elementwise_fma(sa2, b01, v2 * k01));
;                     S23 = __builtin_elementwise_fma(S23, w23, __builtin_elementwise_fma(sa2, b23, v2 * k23));
;                     f32x2v py = S01 * r01; py = __builtin_elementwise_fma(S23, r23, py);
;                     pyprev = py.x + py.y;
;                 }
;                 __builtin_amdgcn_sched_barrier(0);
;                 if (g + 1 < 16) {
; #pragma unroll
;                     for (int u = 0; u < 2; ++u) { R[u] = Rn[u]; W[u] = Wn[u]; K[u] = Kn[u]; A[u] = An[u]; B[u] = Bn[u]; V[u] = Vn[u]; }
	v_pk_mul_f32 v[114:115], v[46:47], v[90:91]
	v_pk_mul_f32 v[118:119], v[46:47], v[86:87]
	v_pk_fma_f32 v[114:115], v[48:49], v[92:93], v[114:115]
	v_pk_fma_f32 v[118:119], v[48:49], v[88:89], v[118:119]
	v_add_f32_e32 v116, v114, v115
	v_add_f32_e32 v132, v118, v119
	v_pk_mul_f32 v[120:121], v[102:103], v[110:111] op_sel_hi:[1,0]
	v_add_f32_dpp v116, v116, v116 quad_perm:[1,0,3,2] row_mask:0xf bank_mask:0xf bound_ctrl:1
	v_pk_mul_f32 v[122:123], v[104:105], v[110:111] op_sel_hi:[1,0]
	v_pk_fma_f32 v[124:125], v[46:47], v[94:95], v[120:121]
	v_add_f32_dpp v116, v116, v116 quad_perm:[2,3,0,1] row_mask:0xf bank_mask:0xf bound_ctrl:1
	v_pk_fma_f32 v[126:127], v[48:49], v[96:97], v[122:123]
	v_cndmask_b32_e64 v137, v129, v130, s[8:9]
	v_add_f32_dpp v116, v116, v116 row_ror:4 row_mask:0xf bank_mask:0xf bound_ctrl:1
	v_cndmask_b32_e64 v186, v130, v129, s[8:9]
	s_nop 1
	v_add_f32_dpp v187, v186, v137 quad_perm:[1,0,3,2] row_mask:0xf bank_mask:0xf bound_ctrl:1
	v_add_f32_dpp v116, v116, v116 row_ror:8 row_mask:0xf bank_mask:0xf bound_ctrl:1
	v_pk_fma_f32 v[46:47], v[116:117], v[98:99], v[124:125] op_sel_hi:[0,1,1]
	v_pk_fma_f32 v[48:49], v[116:117], v[100:101], v[126:127] op_sel_hi:[0,1,1]
	ds_read_b128 v[70:73], v212 offset:38400
	ds_read_b128 v[82:85], v212 offset:22016
	ds_read_b128 v[74:77], v212 offset:13824
	ds_read_b128 v[78:81], v212 offset:46592
	ds_read_b128 v[86:89], v212 offset:5632
	ds_read2st64_b32 v[112:113], v213 offset0:118 offset1:119
	s_waitcnt lgkmcnt(6)
	v_pk_mul_f32 v[114:115], v[46:47], v[50:51]
	v_pk_mul_f32 v[118:119], v[46:47], v[106:107]
	v_pk_fma_f32 v[114:115], v[48:49], v[52:53], v[114:115]
	v_pk_fma_f32 v[118:119], v[48:49], v[108:109], v[118:119]
	v_add_f32_e32 v116, v114, v115
	v_add_f32_e32 v133, v118, v119
	v_pk_mul_f32 v[120:121], v[62:63], v[110:111] op_sel:[0,1] op_sel_hi:[1,1]
	v_add_f32_dpp v116, v116, v116 quad_perm:[1,0,3,2] row_mask:0xf bank_mask:0xf bound_ctrl:1
	v_pk_mul_f32 v[122:123], v[64:65], v[110:111] op_sel:[0,1] op_sel_hi:[1,1]
	v_pk_fma_f32 v[124:125], v[46:47], v[54:55], v[120:121]
	v_add_f32_dpp v116, v116, v116 quad_perm:[2,3,0,1] row_mask:0xf bank_mask:0xf bound_ctrl:1
	v_pk_fma_f32 v[126:127], v[48:49], v[56:57], v[122:123]
	v_cndmask_b32_e64 v137, v131, v132, s[8:9]
	v_add_f32_dpp v116, v116, v116 row_ror:4 row_mask:0xf bank_mask:0xf bound_ctrl:1
	v_cndmask_b32_e64 v186, v132, v131, s[8:9]
	s_nop 1
	v_add_f32_dpp v188, v186, v137 quad_perm:[1,0,3,2] row_mask:0xf bank_mask:0xf bound_ctrl:1
	v_add_f32_dpp v116, v116, v116 row_ror:8 row_mask:0xf bank_mask:0xf bound_ctrl:1
	v_pk_fma_f32 v[46:47], v[116:117], v[58:59], v[124:125] op_sel_hi:[0,1,1]
	v_pk_fma_f32 v[48:49], v[116:117], v[60:61], v[126:127] op_sel_hi:[0,1,1]
	ds_read_b128 v[90:93], v212 offset:38656
	ds_read_b128 v[102:105], v212 offset:22272
	ds_read_b128 v[94:97], v212 offset:14080
	ds_read_b128 v[98:101], v212 offset:46848
	ds_read_b128 v[106:109], v212 offset:5888
	s_waitcnt lgkmcnt(5)
	v_pk_mul_f32 v[114:115], v[46:47], v[70:71]
	v_pk_mul_f32 v[118:119], v[46:47], v[66:67]
	v_pk_fma_f32 v[114:115], v[48:49], v[72:73], v[114:115]
	v_pk_fma_f32 v[118:119], v[48:49], v[68:69], v[118:119]
	v_add_f32_e32 v116, v114, v115
	v_add_f32_e32 v134, v118, v119
	v_pk_mul_f32 v[120:121], v[82:83], v[112:113] op_sel_hi:[1,0]
	v_add_f32_dpp v116, v116, v116 quad_perm:[1,0,3,2] row_mask:0xf bank_mask:0xf bound_ctrl:1
	v_pk_mul_f32 v[122:123], v[84:85], v[112:113] op_sel_hi:[1,0]
	v_pk_fma_f32 v[124:125], v[46:47], v[74:75], v[120:121]
	v_add_f32_dpp v116, v116, v116 quad_perm:[2,3,0,1] row_mask:0xf bank_mask:0xf bound_ctrl:1
	v_pk_fma_f32 v[126:127], v[48:49], v[76:77], v[122:123]
	v_cndmask_b32_e32 v137, v187, v188, vcc
	v_add_f32_dpp v116, v116, v116 row_ror:4 row_mask:0xf bank_mask:0xf bound_ctrl:1
	v_cndmask_b32_e32 v186, v188, v187, vcc
	s_nop 1
	v_add_f32_dpp v189, v186, v137 quad_perm:[2,3,0,1] row_mask:0xf bank_mask:0xf bound_ctrl:1
	v_add_f32_dpp v116, v116, v116 row_ror:8 row_mask:0xf bank_mask:0xf bound_ctrl:1
	v_pk_fma_f32 v[46:47], v[116:117], v[78:79], v[124:125] op_sel_hi:[0,1,1]
	v_pk_fma_f32 v[48:49], v[116:117], v[80:81], v[126:127] op_sel_hi:[0,1,1]
	ds_read_b128 v[50:53], v212 offset:38912
	ds_read_b128 v[62:65], v212 offset:22528
	ds_read_b128 v[54:57], v212 offset:14336
	ds_read_b128 v[58:61], v212 offset:47104
	ds_read_b128 v[66:69], v212 offset:6144
	ds_read2st64_b32 v[110:111], v213 offset0:120 offset1:121
	s_waitcnt lgkmcnt(6)
	v_pk_mul_f32 v[114:115], v[46:47], v[90:91]
	v_pk_mul_f32 v[118:119], v[46:47], v[86:87]
	v_pk_fma_f32 v[114:115], v[48:49], v[92:93], v[114:115]
	v_pk_fma_f32 v[118:119], v[48:49], v[88:89], v[118:119]
	v_add_f32_e32 v116, v114, v115
	v_add_f32_e32 v135, v118, v119
	v_pk_mul_f32 v[120:121], v[102:103], v[112:113] op_sel:[0,1] op_sel_hi:[1,1]
	v_add_f32_dpp v116, v116, v116 quad_perm:[1,0,3,2] row_mask:0xf bank_mask:0xf bound_ctrl:1
	v_pk_mul_f32 v[122:123], v[104:105], v[112:113] op_sel:[0,1] op_sel_hi:[1,1]
	v_pk_fma_f32 v[124:125], v[46:47], v[94:95], v[120:121]
	v_add_f32_dpp v116, v116, v116 quad_perm:[2,3,0,1] row_mask:0xf bank_mask:0xf bound_ctrl:1
	v_pk_fma_f32 v[126:127], v[48:49], v[96:97], v[122:123]
	v_add_f32_dpp v189, v189, v189 row_ror:4 row_mask:0xf bank_mask:0xf bound_ctrl:1
	v_add_f32_dpp v116, v116, v116 row_ror:4 row_mask:0xf bank_mask:0xf bound_ctrl:1
	s_nop 0
	v_add_f32_dpp v189, v189, v189 row_ror:8 row_mask:0xf bank_mask:0xf bound_ctrl:1
	ds_write_b32 v211, v189 offset:1024
	v_add_f32_dpp v116, v116, v116 row_ror:8 row_mask:0xf bank_mask:0xf bound_ctrl:1
	v_pk_fma_f32 v[46:47], v[116:117], v[98:99], v[124:125] op_sel_hi:[0,1,1]
	v_pk_fma_f32 v[48:49], v[116:117], v[100:101], v[126:127] op_sel_hi:[0,1,1]
	ds_read_b128 v[70:73], v212 offset:39168
	ds_read_b128 v[82:85], v212 offset:22784
	ds_read_b128 v[74:77], v212 offset:14592
	ds_read_b128 v[78:81], v212 offset:47360
	ds_read_b128 v[86:89], v212 offset:6400
	s_waitcnt lgkmcnt(6)
; __device__ __forceinline__ void rwkv_prompt_unit(const Params& p, int l, int b, int h, int ibase, float* sf) {
;     ...
;             for (int g = 0; g < 16; ++g) {
;                 f32x4 Rn[2], Wn[2], Kn[2], An[2], Bn[2]; float Vn[2];
;                 if (g + 1 < 16) RW_LOAD(Rn, Wn, Kn, An, Bn, Vn, g + 1);
;                 __builtin_amdgcn_sched_barrier(0);
; #pragma unroll
;                 for (int u = 0; u < 2; ++u) {
;                     const f32x2v a01 = {A[u].x, A[u].y}, a23 = {A[u].z, A[u].w}, w01 = {W[u].x, W[u].y}, w23 = {W[u].z, W[u].w}, b01 = {B[u].x, B[u].y}, b23 = {B[u].z, B[u].w};
;                     const f32x2v k01 = {K[u].x, K[u].y}, k23 = {K[u].z, K[u].w}, r01 = {R[u].x, R[u].y}, r23 = {R[u].z, R[u].w};
;                     f32x2v pa = S01 * a01; pa = __builtin_elementwise_fma(S23, a23, pa);
;                     float ra = pa.x + pa.y, rb = pyprev;
;                     ra += dppf<0xB1, 0xF>(ra); rb += dppf<0xB1, 0xF>(rb);
;                     ra += dppf<0x4E, 0xF>(ra); rb += dppf<0x4E, 0xF>(rb);
;                     ra += dppf<0x124, 0xF>(ra); rb += dppf<0x124, 0xF>(rb);
;                     ra += dppf<0x128, 0xF>(ra); rb += dppf<0x128, 0xF>(rb);
;                     if ((g * 2 + u) > 0 && (lane & 15) == 0) sY[(g * 2 + u - 1) * 16 + rl] = rb;
;                     const f32x2v sa2 = {ra, ra}, v2 = {V[u], V[u]};
;                     S01 = __builtin_elementwise_fma(S01, w01, __builtin_elementwise_fma(sa2, b01, v2 * k01));
;                     S23 = __builtin_elementwise_fma(S23, w23, __builtin_elementwise_fma(sa2, b23, v2 * k23));
;                     f32x2v py = S01 * r01; py = __builtin_elementwise_fma(S23, r23, py);
;                     pyprev = py.x + py.y;
;                 }
;                 __builtin_amdgcn_sched_barrier(0);
;                 if (g + 1 < 16) {
; #pragma unroll
;                     for (int u = 0; u < 2; ++u) { R[u] = Rn[u]; W[u] = Wn[u]; K[u] = Kn[u]; A[u] = An[u]; B[u] = Bn[u]; V[u] = Vn[u]; }
	v_pk_mul_f32 v[114:115], v[46:47], v[50:51]
	v_pk_mul_f32 v[118:119], v[46:47], v[106:107]
	v_pk_fma_f32 v[114:115], v[48:49], v[52:53], v[114:115]
	v_pk_fma_f32 v[118:119], v[48:49], v[108:109], v[118:119]
	v_add_f32_e32 v116, v114, v115
	v_add_f32_e32 v136, v118, v119
	v_pk_mul_f32 v[120:121], v[62:63], v[110:111] op_sel_hi:[1,0]
	v_add_f32_dpp v116, v116, v116 quad_perm:[1,0,3,2] row_mask:0xf bank_mask:0xf bound_ctrl:1
	v_pk_mul_f32 v[122:123], v[64:65], v[110:111] op_sel_hi:[1,0]
	v_pk_fma_f32 v[124:125], v[46:47], v[54:55], v[120:121]
	v_add_f32_dpp v116, v116, v116 quad_perm:[2,3,0,1] row_mask:0xf bank_mask:0xf bound_ctrl:1
	v_pk_fma_f32 v[126:127], v[48:49], v[56:57], v[122:123]
	v_cndmask_b32_e64 v137, v133, v134, s[8:9]
	v_add_f32_dpp v116, v116, v116 row_ror:4 row_mask:0xf bank_mask:0xf bound_ctrl:1
	v_cndmask_b32_e64 v186, v134, v133, s[8:9]
	s_nop 1
	v_add_f32_dpp v187, v186, v137 quad_perm:[1,0,3,2] row_mask:0xf bank_mask:0xf bound_ctrl:1
	v_add_f32_dpp v116, v116, v116 row_ror:8 row_mask:0xf bank_mask:0xf bound_ctrl:1
	v_pk_fma_f32 v[46:47], v[116:117], v[58:59], v[124:125] op_sel_hi:[0,1,1]
	v_pk_fma_f32 v[48:49], v[116:117], v[60:61], v[126:127] op_sel_hi:[0,1,1]
	ds_read_b128 v[90:93], v212 offset:39424
	ds_read_b128 v[102:105], v212 offset:23040
	ds_read_b128 v[94:97], v212 offset:14848
	ds_read_b128 v[98:101], v212 offset:47616
	ds_read_b128 v[106:109], v212 offset:6656
	ds_read2st64_b32 v[112:113], v213 offset0:122 offset1:123
	s_waitcnt lgkmcnt(6)
	v_pk_mul_f32 v[114:115], v[46:47], v[70:71]
	v_pk_mul_f32 v[118:119], v[46:47], v[66:67]
	v_pk_fma_f32 v[114:115], v[48:49], v[72:73], v[114:115]
	v_pk_fma_f32 v[118:119], v[48:49], v[68:69], v[118:119]
	v_add_f32_e32 v116, v114, v115
	v_add_f32_e32 v129, v118, v119
	v_pk_mul_f32 v[120:121], v[82:83], v[110:111] op_sel:[0,1] op_sel_hi:[1,1]
	v_add_f32_dpp v116, v116, v116 quad_perm:[1,0,3,2] row_mask:0xf bank_mask:0xf bound_ctrl:1
	v_pk_mul_f32 v[122:123], v[84:85], v[110:111] op_sel:[0,1] op_sel_hi:[1,1]
	v_pk_fma_f32 v[124:125], v[46:47], v[74:75], v[120:121]
	v_add_f32_dpp v116, v116, v116 quad_perm:[2,3,0,1] row_mask:0xf bank_mask:0xf bound_ctrl:1
	v_pk_fma_f32 v[126:127], v[48:49], v[76:77], v[122:123]
	v_cndmask_b32_e64 v137, v135, v136, s[8:9]
	v_add_f32_dpp v116, v116, v116 row_ror:4 row_mask:0xf bank_mask:0xf bound_ctrl:1
	v_cndmask_b32_e64 v186, v136, v135, s[8:9]
	s_nop 1
	v_add_f32_dpp v188, v186, v137 quad_perm:[1,0,3,2] row_mask:0xf bank_mask:0xf bound_ctrl:1
	v_add_f32_dpp v116, v116, v116 row_ror:8 row_mask:0xf bank_mask:0xf bound_ctrl:1
	v_pk_fma_f32 v[46:47], v[116:117], v[78:79], v[124:125] op_sel_hi:[0,1,1]
	v_pk_fma_f32 v[48:49], v[116:117], v[80:81], v[126:127] op_sel_hi:[0,1,1]
	ds_read_b128 v[50:53], v212 offset:39680
	ds_read_b128 v[62:65], v212 offset:23296
	ds_read_b128 v[54:57], v212 offset:15104
	ds_read_b128 v[58:61], v212 offset:47872
	ds_read_b128 v[66:69], v212 offset:6912
	s_waitcnt lgkmcnt(5)
	v_pk_mul_f32 v[114:115], v[46:47], v[90:91]
	v_pk_mul_f32 v[118:119], v[46:47], v[86:87]
	v_pk_fma_f32 v[114:115], v[48:49], v[92:93], v[114:115]
	v_pk_fma_f32 v[118:119], v[48:49], v[88:89], v[118:119]
	v_add_f32_e32 v116, v114, v115
	v_add_f32_e32 v130, v118, v119
	v_pk_mul_f32 v[120:121], v[102:103], v[112:113] op_sel_hi:[1,0]
	v_add_f32_dpp v116, v116, v116 quad_perm:[1,0,3,2] row_mask:0xf bank_mask:0xf bound_ctrl:1
	v_pk_mul_f32 v[122:123], v[104:105], v[112:113] op_sel_hi:[1,0]
	v_pk_fma_f32 v[124:125], v[46:47], v[94:95], v[120:121]
	v_add_f32_dpp v116, v116, v116 quad_perm:[2,3,0,1] row_mask:0xf bank_mask:0xf bound_ctrl:1
	v_pk_fma_f32 v[126:127], v[48:49], v[96:97], v[122:123]
	v_cndmask_b32_e32 v137, v187, v188, vcc
	v_add_f32_dpp v116, v116, v116 row_ror:4 row_mask:0xf bank_mask:0xf bound_ctrl:1
	v_cndmask_b32_e32 v186, v188, v187, vcc
	s_nop 1
	v_add_f32_dpp v189, v186, v137 quad_perm:[2,3,0,1] row_mask:0xf bank_mask:0xf bound_ctrl:1
	v_add_f32_dpp v116, v116, v116 row_ror:8 row_mask:0xf bank_mask:0xf bound_ctrl:1
	v_pk_fma_f32 v[46:47], v[116:117], v[98:99], v[124:125] op_sel_hi:[0,1,1]
	v_pk_fma_f32 v[48:49], v[116:117], v[100:101], v[126:127] op_sel_hi:[0,1,1]
	ds_read_b128 v[70:73], v212 offset:39936
	ds_read_b128 v[82:85], v212 offset:23552
	ds_read_b128 v[74:77], v212 offset:15360
	ds_read_b128 v[78:81], v212 offset:48128
	ds_read_b128 v[86:89], v212 offset:7168
	ds_read2st64_b32 v[110:111], v213 offset0:124 offset1:125
	s_waitcnt lgkmcnt(6)
	v_pk_mul_f32 v[114:115], v[46:47], v[50:51]
	v_pk_mul_f32 v[118:119], v[46:47], v[106:107]
	v_pk_fma_f32 v[114:115], v[48:49], v[52:53], v[114:115]
	v_pk_fma_f32 v[118:119], v[48:49], v[108:109], v[118:119]
	v_add_f32_e32 v116, v114, v115
	v_add_f32_e32 v131, v118, v119
	v_pk_mul_f32 v[120:121], v[62:63], v[112:113] op_sel:[0,1] op_sel_hi:[1,1]
	v_add_f32_dpp v116, v116, v116 quad_perm:[1,0,3,2] row_mask:0xf bank_mask:0xf bound_ctrl:1
	v_pk_mul_f32 v[122:123], v[64:65], v[112:113] op_sel:[0,1] op_sel_hi:[1,1]
	v_pk_fma_f32 v[124:125], v[46:47], v[54:55], v[120:121]
	v_add_f32_dpp v116, v116, v116 quad_perm:[2,3,0,1] row_mask:0xf bank_mask:0xf bound_ctrl:1
	v_pk_fma_f32 v[126:127], v[48:49], v[56:57], v[122:123]
	v_add_f32_dpp v189, v189, v189 row_ror:4 row_mask:0xf bank_mask:0xf bound_ctrl:1
	v_add_f32_dpp v116, v116, v116 row_ror:4 row_mask:0xf bank_mask:0xf bound_ctrl:1
	s_nop 0
	v_add_f32_dpp v189, v189, v189 row_ror:8 row_mask:0xf bank_mask:0xf bound_ctrl:1
	ds_write_b32 v211, v189 offset:1280
	v_add_f32_dpp v116, v116, v116 row_ror:8 row_mask:0xf bank_mask:0xf bound_ctrl:1
	v_pk_fma_f32 v[46:47], v[116:117], v[58:59], v[124:125] op_sel_hi:[0,1,1]
	v_pk_fma_f32 v[48:49], v[116:117], v[60:61], v[126:127] op_sel_hi:[0,1,1]
	ds_read_b128 v[90:93], v212 offset:40192
	ds_read_b128 v[102:105], v212 offset:23808
	ds_read_b128 v[94:97], v212 offset:15616
	ds_read_b128 v[98:101], v212 offset:48384
	ds_read_b128 v[106:109], v212 offset:7424
	s_waitcnt lgkmcnt(6)
; __device__ __forceinline__ float row_sum16(float x) { x += __shfl_xor(x, 1); x += __shfl_xor(x, 2); x += __shfl_xor(x, 4); x += __shfl_xor(x, 8); return x; }
; __device__ __forceinline__ void rwkv_prompt_unit(const Params& p, int l, int b, int h, int ibase, float* sf) {
;     ...
;             for (int g = 0; g < 16; ++g) {
;                 f32x4 Rn[2], Wn[2], Kn[2], An[2], Bn[2]; float Vn[2];
;                 if (g + 1 < 16) RW_LOAD(Rn, Wn, Kn, An, Bn, Vn, g + 1);
;                 __builtin_amdgcn_sched_barrier(0);
; #pragma unroll
;                 for (int u = 0; u < 2; ++u) {
;                     const f32x2v a01 = {A[u].x, A[u].y}, a23 = {A[u].z, A[u].w}, w01 = {W[u].x, W[u].y}, w23 = {W[u].z, W[u].w}, b01 = {B[u].x, B[u].y}, b23 = {B[u].z, B[u].w};
;                     const f32x2v k01 = {K[u].x, K[u].y}, k23 = {K[u].z, K[u].w}, r01 = {R[u].x, R[u].y}, r23 = {R[u].z, R[u].w};
;                     f32x2v pa = S01 * a01; pa = __builtin_elementwise_fma(S23, a23, pa);
;                     float ra = pa.x + pa.y, rb = pyprev;
;                     ra += dppf<0xB1, 0xF>(ra); rb += dppf<0xB1, 0xF>(rb);
;                     ra += dppf<0x4E, 0xF>(ra); rb += dppf<0x4E, 0xF>(rb);
;                     ra += dppf<0x124, 0xF>(ra); rb += dppf<0x124, 0xF>(rb);
;                     ra += dppf<0x128, 0xF>(ra); rb += dppf<0x128, 0xF>(rb);
;                     if ((g * 2 + u) > 0 && (lane & 15) == 0) sY[(g * 2 + u - 1) * 16 + rl] = rb;
;                     const f32x2v sa2 = {ra, ra}, v2 = {V[u], V[u]};
;                     S01 = __builtin_elementwise_fma(S01, w01, __builtin_elementwise_fma(sa2, b01, v2 * k01));
;                     S23 = __builtin_elementwise_fma(S23, w23, __builtin_elementwise_fma(sa2, b23, v2 * k23));
;                     f32x2v py = S01 * r01; py = __builtin_elementwise_fma(S23, r23, py);
;                     pyprev = py.x + py.y;
;                 }
;                 __builtin_amdgcn_sched_barrier(0);
;                 if (g + 1 < 16) {
; #pragma unroll
;                     for (int u = 0; u < 2; ++u) { R[u] = Rn[u]; W[u] = Wn[u]; K[u] = Kn[u]; A[u] = An[u]; B[u] = Bn[u]; V[u] = Vn[u]; }
;                 }
;             }
;     ...
;             { const float yl = row_sum16(pyprev); if ((lane & 15) == 0) sY[31 * 16 + rl] = yl; }
	v_pk_mul_f32 v[114:115], v[46:47], v[70:71]
	v_pk_mul_f32 v[118:119], v[46:47], v[66:67]
	v_pk_fma_f32 v[114:115], v[48:49], v[72:73], v[114:115]
	v_pk_fma_f32 v[118:119], v[48:49], v[68:69], v[118:119]
	v_add_f32_e32 v116, v114, v115
	v_add_f32_e32 v132, v118, v119
	v_pk_mul_f32 v[120:121], v[82:83], v[110:111] op_sel_hi:[1,0]
	v_add_f32_dpp v116, v116, v116 quad_perm:[1,0,3,2] row_mask:0xf bank_mask:0xf bound_ctrl:1
	v_pk_mul_f32 v[122:123], v[84:85], v[110:111] op_sel_hi:[1,0]
	v_pk_fma_f32 v[124:125], v[46:47], v[74:75], v[120:121]
	v_add_f32_dpp v116, v116, v116 quad_perm:[2,3,0,1] row_mask:0xf bank_mask:0xf bound_ctrl:1
	v_pk_fma_f32 v[126:127], v[48:49], v[76:77], v[122:123]
	v_cndmask_b32_e64 v137, v129, v130, s[8:9]
	v_add_f32_dpp v116, v116, v116 row_ror:4 row_mask:0xf bank_mask:0xf bound_ctrl:1
	v_cndmask_b32_e64 v186, v130, v129, s[8:9]
	s_nop 1
	v_add_f32_dpp v187, v186, v137 quad_perm:[1,0,3,2] row_mask:0xf bank_mask:0xf bound_ctrl:1
	v_add_f32_dpp v116, v116, v116 row_ror:8 row_mask:0xf bank_mask:0xf bound_ctrl:1
	v_pk_fma_f32 v[46:47], v[116:117], v[78:79], v[124:125] op_sel_hi:[0,1,1]
	v_pk_fma_f32 v[48:49], v[116:117], v[80:81], v[126:127] op_sel_hi:[0,1,1]
	ds_read_b128 v[50:53], v212 offset:40448
	ds_read_b128 v[62:65], v212 offset:24064
	ds_read_b128 v[54:57], v212 offset:15872
	ds_read_b128 v[58:61], v212 offset:48640
	ds_read_b128 v[66:69], v212 offset:7680
	ds_read2st64_b32 v[112:113], v213 offset0:126 offset1:127
	s_waitcnt lgkmcnt(6)
	v_pk_mul_f32 v[114:115], v[46:47], v[90:91]
	v_pk_mul_f32 v[118:119], v[46:47], v[86:87]
	v_pk_fma_f32 v[114:115], v[48:49], v[92:93], v[114:115]
	v_pk_fma_f32 v[118:119], v[48:49], v[88:89], v[118:119]
	v_add_f32_e32 v116, v114, v115
	v_add_f32_e32 v133, v118, v119
	v_pk_mul_f32 v[120:121], v[102:103], v[110:111] op_sel:[0,1] op_sel_hi:[1,1]
	v_add_f32_dpp v116, v116, v116 quad_perm:[1,0,3,2] row_mask:0xf bank_mask:0xf bound_ctrl:1
	v_pk_mul_f32 v[122:123], v[104:105], v[110:111] op_sel:[0,1] op_sel_hi:[1,1]
	v_pk_fma_f32 v[124:125], v[46:47], v[94:95], v[120:121]
	v_add_f32_dpp v116, v116, v116 quad_perm:[2,3,0,1] row_mask:0xf bank_mask:0xf bound_ctrl:1
	v_pk_fma_f32 v[126:127], v[48:49], v[96:97], v[122:123]
	v_cndmask_b32_e64 v137, v131, v132, s[8:9]
	v_add_f32_dpp v116, v116, v116 row_ror:4 row_mask:0xf bank_mask:0xf bound_ctrl:1
	v_cndmask_b32_e64 v186, v132, v131, s[8:9]
	s_nop 1
	v_add_f32_dpp v188, v186, v137 quad_perm:[1,0,3,2] row_mask:0xf bank_mask:0xf bound_ctrl:1
	v_add_f32_dpp v116, v116, v116 row_ror:8 row_mask:0xf bank_mask:0xf bound_ctrl:1
	v_pk_fma_f32 v[46:47], v[116:117], v[98:99], v[124:125] op_sel_hi:[0,1,1]
	v_pk_fma_f32 v[48:49], v[116:117], v[100:101], v[126:127] op_sel_hi:[0,1,1]
	ds_read_b128 v[70:73], v212 offset:40704
	ds_read_b128 v[82:85], v212 offset:24320
	ds_read_b128 v[74:77], v212 offset:16128
	ds_read_b128 v[78:81], v212 offset:48896
	ds_read_b128 v[86:89], v212 offset:7936
	s_waitcnt lgkmcnt(5)
	v_pk_mul_f32 v[114:115], v[46:47], v[50:51]
	v_pk_mul_f32 v[118:119], v[46:47], v[106:107]
	v_pk_fma_f32 v[114:115], v[48:49], v[52:53], v[114:115]
	v_pk_fma_f32 v[118:119], v[48:49], v[108:109], v[118:119]
	v_add_f32_e32 v116, v114, v115
	v_add_f32_e32 v134, v118, v119
	v_pk_mul_f32 v[120:121], v[62:63], v[112:113] op_sel_hi:[1,0]
	v_add_f32_dpp v116, v116, v116 quad_perm:[1,0,3,2] row_mask:0xf bank_mask:0xf bound_ctrl:1
	v_pk_mul_f32 v[122:123], v[64:65], v[112:113] op_sel_hi:[1,0]
	v_pk_fma_f32 v[124:125], v[46:47], v[54:55], v[120:121]
	v_add_f32_dpp v116, v116, v116 quad_perm:[2,3,0,1] row_mask:0xf bank_mask:0xf bound_ctrl:1
	v_pk_fma_f32 v[126:127], v[48:49], v[56:57], v[122:123]
	v_cndmask_b32_e32 v137, v187, v188, vcc
	v_add_f32_dpp v116, v116, v116 row_ror:4 row_mask:0xf bank_mask:0xf bound_ctrl:1
	v_cndmask_b32_e32 v186, v188, v187, vcc
	s_nop 1
	v_add_f32_dpp v189, v186, v137 quad_perm:[2,3,0,1] row_mask:0xf bank_mask:0xf bound_ctrl:1
	v_add_f32_dpp v116, v116, v116 row_ror:8 row_mask:0xf bank_mask:0xf bound_ctrl:1
	v_pk_fma_f32 v[46:47], v[116:117], v[58:59], v[124:125] op_sel_hi:[0,1,1]
	v_pk_fma_f32 v[48:49], v[116:117], v[60:61], v[126:127] op_sel_hi:[0,1,1]
	s_waitcnt lgkmcnt(0)
	v_pk_mul_f32 v[114:115], v[46:47], v[70:71]
	v_pk_mul_f32 v[118:119], v[46:47], v[66:67]
	v_pk_fma_f32 v[114:115], v[48:49], v[72:73], v[114:115]
	v_pk_fma_f32 v[118:119], v[48:49], v[68:69], v[118:119]
	v_add_f32_e32 v116, v114, v115
	v_add_f32_e32 v135, v118, v119
	v_pk_mul_f32 v[120:121], v[82:83], v[112:113] op_sel:[0,1] op_sel_hi:[1,1]
	v_add_f32_dpp v116, v116, v116 quad_perm:[1,0,3,2] row_mask:0xf bank_mask:0xf bound_ctrl:1
	v_pk_mul_f32 v[122:123], v[84:85], v[112:113] op_sel:[0,1] op_sel_hi:[1,1]
	v_pk_fma_f32 v[124:125], v[46:47], v[74:75], v[120:121]
	v_add_f32_dpp v116, v116, v116 quad_perm:[2,3,0,1] row_mask:0xf bank_mask:0xf bound_ctrl:1
	v_pk_fma_f32 v[126:127], v[48:49], v[76:77], v[122:123]
	v_add_f32_dpp v189, v189, v189 row_ror:4 row_mask:0xf bank_mask:0xf bound_ctrl:1
	v_add_f32_dpp v116, v116, v116 row_ror:4 row_mask:0xf bank_mask:0xf bound_ctrl:1
	s_nop 0
	v_add_f32_dpp v189, v189, v189 row_ror:8 row_mask:0xf bank_mask:0xf bound_ctrl:1
	ds_write_b32 v211, v189 offset:1536
	v_add_f32_dpp v116, v116, v116 row_ror:8 row_mask:0xf bank_mask:0xf bound_ctrl:1
	v_pk_fma_f32 v[46:47], v[116:117], v[78:79], v[124:125] op_sel_hi:[0,1,1]
	v_pk_fma_f32 v[48:49], v[116:117], v[80:81], v[126:127] op_sel_hi:[0,1,1]
	v_pk_mul_f32 v[118:119], v[46:47], v[86:87]
	s_nop 0
	v_pk_fma_f32 v[118:119], v[48:49], v[88:89], v[118:119]
	s_nop 0
	v_add_f32_e32 v136, v118, v119
	v_cndmask_b32_e64 v137, v133, v134, s[8:9]
	v_cndmask_b32_e64 v186, v134, v133, s[8:9]
	s_nop 1
	v_add_f32_dpp v187, v186, v137 quad_perm:[1,0,3,2] row_mask:0xf bank_mask:0xf bound_ctrl:1
	v_cndmask_b32_e64 v137, v135, v136, s[8:9]
	v_cndmask_b32_e64 v186, v136, v135, s[8:9]
	s_nop 1
	v_add_f32_dpp v188, v186, v137 quad_perm:[1,0,3,2] row_mask:0xf bank_mask:0xf bound_ctrl:1
	v_cndmask_b32_e32 v137, v187, v188, vcc
	v_cndmask_b32_e32 v186, v188, v187, vcc
	s_nop 1
	v_add_f32_dpp v189, v186, v137 quad_perm:[2,3,0,1] row_mask:0xf bank_mask:0xf bound_ctrl:1
	s_nop 1
	v_add_f32_dpp v189, v189, v189 row_ror:4 row_mask:0xf bank_mask:0xf bound_ctrl:1
	s_nop 1
	v_add_f32_dpp v189, v189, v189 row_ror:8 row_mask:0xf bank_mask:0xf bound_ctrl:1
	ds_write_b32 v211, v189 offset:1792
	s_setprio 0
	s_branch .LBB0_955
